# removed redundant vmcnt(0) between Q-load groups in SWA/FoX attention prologues
# baseline (speedup 1.0000x reference)
; #define LAS __attribute__((address_space(3)))
; __device__ __forceinline__ float bflo(unsigned w) { return __uint_as_float(w << 16); }
; __device__ __forceinline__ float bfhi(unsigned w) { return __uint_as_float(w & 0xffff0000u); }
;     ...
;     bf16x8 qf[8];
; #pragma unroll
;     for (int ks = 0; ks < 8; ++ks) qf[ks] = *(const bf16x8*)(Qrow + 16 * ks + 8 * hh);
;     f32x16 o[4];
; #pragma unroll
;     for (int db = 0; db < 4; ++db)
; #pragma unroll
;         for (int i = 0; i < 16; ++i) o[db][i] = 0.f;
;     float m = m_init, l = (hh == 0) ? l_init : 0.f;
;     const int pr = (r & ~12) | ((r & 4) << 1) | ((r & 8) >> 1);
;     const unsigned koff = pr * AT_KROW + 16 * hh, voff = AT_KBUF + r * AT_VROW + 16 * hh;
;     const int kkey0 = tid >> 4, kc16 = tid & 15, vd0 = tid >> 3, vc8 = tid & 7;
;     u32x4 kreg[2], vreg[2]; float creg = 0.f;
;     ...
;     float qn = 0.f; bool wdone = false;
;     LAS unsigned* flg = (LAS unsigned*)(lds + 2 * AT_BUF);
;     if (MODE == 0) {
; #pragma unroll
;         for (int ks = 0; ks < 8; ++ks) { const u32x4 qq = __builtin_bit_cast(u32x4, qf[ks]);
;             qn += bflo(qq.x) * bflo(qq.x) + bfhi(qq.x) * bfhi(qq.x) + bflo(qq.y) * bflo(qq.y) + bfhi(qq.y) * bfhi(qq.y) + bflo(qq.z) * bflo(qq.z) + bfhi(qq.z) * bfhi(qq.z) + bflo(qq.w) * bflo(qq.w) + bfhi(qq.w) * bfhi(qq.w); }
;         qn = xsum(qn); qn = sqrtf(qn) * kn * SC * 1.0001f + 1e-3f;
;     }
;     AT_LOAD(kt1 - 1); AT_WRITE(0); __syncthreads();
; __global__ void __launch_bounds__(512, 2) hybrid_fwd(Params p) {
;     ...
;                 for (int si = 0; si < (cc < 64 ? 1 : 3); ++si) {
;                     const int su = cc < 64 ? cc : 64 + (cc - 64) * 3 + si;
;                     const int v = su, kvh = v >> 7, n = (v >> 1) & 63, pr = v & 1;
;                     const int hl = wave >> 2, qh = kvh * 4 + pr * 2 + hl, tq0 = 128 * n + 32 * (wave & 3), t_row = tq0 + (lane & 31);
;                     attn_unit<1>(lds, tid, PROJ + (size_t)t_row * NP + PJ_SQ + qh * 128, PROJ + PJ_SK + kvh * 128, NP, VT + (size_t)(VT_S + kvh * 128) * T_, T_,
;                                  (2 * n - 2) < 0 ? 0 : (2 * n - 2), 2 * n + 2, t_row, tq0, nullptr, p.swa_sinks[l * 8 + qh] * LOG2E, 1.f, t5 + qh * 128,
;                                  O + (size_t)t_row * D_ + 512 + qh * 128);
.LBB0_558:
	s_add_i32 s6, s14, s23
	s_and_b64 s[4:5], exec, s[0:1]
	s_cselect_b32 s6, s12, s6
	s_bfe_u32 s24, s6, 0x60001
	s_ashr_i32 s4, s6, 5
	s_lshl_b32 s5, s6, 1
	s_lshl_b32 s72, s24, 7
	s_and_b32 s4, s4, -4
	s_and_b32 s5, s5, 2
	s_or_b32 s28, s72, s16
	s_or_b32 s4, s4, s5
	v_or_b32_e32 v160, s28, v145
	v_mov_b64_e32 v[0:1], s[8:9]
	s_add_i32 s25, s4, s15
	v_mad_u64_u32 v[146:147], s[4:5], v160, s56, v[0:1]
	s_and_b32 s10, s6, 0xffffff80
	s_lshl_b32 s4, s25, 7
	s_ashr_i32 s11, s10, 31
	s_ashr_i32 s5, s4, 31
	s_lshl_b64 s[6:7], s[10:11], 1
	s_add_u32 s26, s17, s6
	s_addc_u32 s27, s18, s7
	s_lshl_b64 s[10:11], s[10:11], 14
	s_add_u32 s10, s19, s10
	s_addc_u32 s11, s21, s11
	s_lshl_b32 s29, s24, 1
	s_add_i32 s30, s29, -2
	s_cmp_lg_u32 s24, 0
	s_cselect_b32 s24, s30, 0
	s_add_i32 s30, s25, s22
	s_ashr_i32 s31, s30, 31
	s_lshl_b64 s[30:31], s[30:31], 2
	s_add_u32 s30, s60, s30
	s_addc_u32 s31, s61, s31
	v_mov_b32_e32 v5, v144
	global_load_dword v4, v201, s[30:31]
	v_lshl_add_u64 v[0:1], s[4:5], 1, v[146:147]
	v_bfe_u32 v161, v5, 5, 1
	v_lshlrev_b32_e32 v200, 4, v161
	v_lshl_add_u64 v[0:1], v[0:1], 0, v[200:201]
	s_mov_b32 s25, 0x1f600000
	s_mov_b64 s[30:31], 0x1f600800
	v_add_co_u32_e32 v10, vcc, s25, v0
	v_ashrrev_i32_e32 v6, 4, v5
	s_or_b32 s25, s29, 1
	v_lshl_add_u64 v[8:9], v[0:1], 0, s[30:31]
	v_addc_co_u32_e32 v11, vcc, 0, v1, vcc
	v_lshl_add_u32 v13, s25, 6, v6
	v_mov_b64_e32 v[0:1], s[26:27]
	v_mad_i64_i32 v[2:3], s[26:27], v13, s56, v[0:1]
	v_lshlrev_b32_e32 v14, 4, v5
	v_add_u32_e32 v13, 32, v13
	v_ashrrev_i32_e32 v12, 3, v5
	v_and_b32_e32 v148, 0xf0, v14
	v_mov_b32_e32 v149, v201
	v_mad_i64_i32 v[0:1], s[26:27], v13, s56, v[0:1]
	flat_load_dwordx4 v[96:99], v[8:9] offset:32
	flat_load_dwordx4 v[100:103], v[8:9] offset:64
	flat_load_dwordx4 v[104:107], v[8:9] offset:96
	flat_load_dwordx4 v[108:111], v[8:9] offset:128
	v_lshl_add_u64 v[2:3], v[2:3], 0, v[148:149]
	v_lshl_add_u64 v[0:1], v[0:1], 0, v[148:149]
	v_ashrrev_i32_e32 v13, 31, v12
	s_nop 0
	flat_load_dwordx4 v[112:115], v[2:3]
	flat_load_dwordx4 v[116:119], v[0:1]
	v_lshlrev_b64 v[0:1], 14, v[12:13]
	v_lshl_add_u64 v[2:3], s[10:11], 0, v[0:1]
	s_mov_b64 s[10:11], 0x800000
	v_and_b32_e32 v7, 7, v5
	v_lshl_add_u64 v[0:1], v[2:3], 0, s[10:11]
	s_lshl_b32 s10, s25, 7
	s_mov_b32 s11, s73
	s_mov_b64 s[26:27], 0x900000
	v_lshl_add_u64 v[14:15], v[0:1], 0, s[10:11]
	v_lshlrev_b32_e32 v150, 4, v7
	v_mov_b32_e32 v151, v201
	v_lshl_add_u64 v[2:3], v[2:3], 0, s[26:27]
	v_lshl_add_u64 v[14:15], v[14:15], 0, v[150:151]
	v_lshl_add_u64 v[16:17], v[2:3], 0, s[10:11]
	v_lshl_add_u64 v[16:17], v[16:17], 0, v[150:151]
	flat_load_dwordx4 v[136:139], v[14:15]
	flat_load_dwordx4 v[140:143], v[16:17]
	flat_load_dwordx4 v[120:123], v[8:9] offset:160
	flat_load_dwordx4 v[124:127], v[8:9] offset:192
	flat_load_dwordx4 v[128:131], v[10:11] offset:2048
	flat_load_dwordx4 v[132:135], v[8:9] offset:224
	s_movk_i32 s10, 0x110
	v_cmp_eq_u32_e32 vcc, 0, v161
	v_mul_lo_u32 v151, v6, s10
	v_mov_b32_e32 v15, 0
	s_cmp_lt_u32 s29, s24
	v_cndmask_b32_e64 v149, 0, 1.0, vcc
	v_mul_lo_u32 v162, v12, s83
	v_add3_u32 v8, 0, v151, v148
	v_add3_u32 v9, 0, v162, v150
	s_waitcnt vmcnt(0) lgkmcnt(0)
	ds_write_b128 v8, v[112:115]
	ds_write_b128 v8, v[116:119] offset:8704
	ds_write_b128 v9, v[136:139] offset:17408
	ds_write_b128 v9, v[140:143] offset:26624
	s_waitcnt lgkmcnt(0)
	s_barrier
	s_cbranch_scc1 .LBB0_556
	v_and_b32_e32 v8, 31, v5
	v_and_b32_e32 v9, 19, v5
	v_lshlrev_b32_e32 v10, 1, v5
	v_lshrrev_b32_e32 v5, 1, v5
	v_and_b32_e32 v10, 8, v10
	v_and_b32_e32 v5, 4, v5
	v_lshlrev_b32_e32 v7, 3, v7
	v_or3_b32 v5, v9, v10, v5
	v_mul_u32_u24_e32 v163, 0x90, v8
	s_lshl_b32 s10, s4, 2
	v_lshlrev_b32_e32 v8, 1, v7
	v_mov_b32_e32 v9, v201
	s_add_i32 s26, s10, 0
	v_lshl_add_u64 v[152:153], v[0:1], 0, v[8:9]
	v_lshl_add_u64 v[154:155], v[2:3], 0, v[8:9]
	v_mov_b32_e32 v0, s16
	s_movk_i32 s10, 0x78
	v_add_u32_e32 v2, s72, v6
	s_add_i32 s26, s26, 0x12000
	s_or_b32 s27, s28, 31
	s_addk_i32 s28, 0xff80
	v_mad_u32_u24 v167, v161, s10, v0
	v_add_u32_e32 v0, 32, v2
	v_mad_i64_i32 v[0:1], s[10:11], v0, s56, 0
	s_add_u32 s6, s17, s6
	v_or_b32_e32 v0, v0, v148
	s_addc_u32 s7, s18, s7
	v_lshl_add_u64 v[156:157], s[6:7], 0, v[0:1]
	v_mad_i64_i32 v[0:1], s[10:11], v2, s56, 0
	v_mul_u32_u24_e32 v5, 0x110, v5
	v_or_b32_e32 v0, v0, v148
	v_mov_b32_e32 v48, 0
	v_add_u32_e32 v164, v5, v200
	v_add_u32_e32 v165, 0x2400, v162
	v_mul_f32_e32 v168, 0x3fb8aa3b, v4
	v_mad_i32_i24 v166, v161, -8, s16
	v_lshl_add_u64 v[158:159], s[6:7], 0, v[0:1]
	v_mov_b32_e32 v49, v48
	v_mov_b32_e32 v50, v48
	v_mov_b32_e32 v51, v48
	v_mov_b32_e32 v52, v48
	v_mov_b32_e32 v53, v48
	v_mov_b32_e32 v54, v48
	v_mov_b32_e32 v55, v48
	v_mov_b32_e32 v56, v48
	v_mov_b32_e32 v57, v48
	v_mov_b32_e32 v58, v48
	v_mov_b32_e32 v59, v48
	v_mov_b32_e32 v60, v48
	v_mov_b32_e32 v61, v48
	v_mov_b32_e32 v62, v48
	v_mov_b32_e32 v63, v48
	v_mov_b32_e32 v32, v48
	v_mov_b32_e32 v33, v48
	v_mov_b32_e32 v34, v48
	v_mov_b32_e32 v35, v48
	v_mov_b32_e32 v36, v48
	v_mov_b32_e32 v37, v48
	v_mov_b32_e32 v38, v48
	v_mov_b32_e32 v39, v48
	v_mov_b32_e32 v40, v48
	v_mov_b32_e32 v41, v48
	v_mov_b32_e32 v42, v48
	v_mov_b32_e32 v43, v48
	v_mov_b32_e32 v44, v48
	v_mov_b32_e32 v45, v48
	v_mov_b32_e32 v46, v48
	v_mov_b32_e32 v47, v48
	v_mov_b32_e32 v16, v48
	v_mov_b32_e32 v17, v48
	v_mov_b32_e32 v18, v48
	v_mov_b32_e32 v19, v48
	v_mov_b32_e32 v20, v48
	v_mov_b32_e32 v21, v48
	v_mov_b32_e32 v22, v48
	v_mov_b32_e32 v23, v48
	v_mov_b32_e32 v24, v48
	v_mov_b32_e32 v25, v48
	v_mov_b32_e32 v26, v48
	v_mov_b32_e32 v27, v48
	v_mov_b32_e32 v28, v48
	v_mov_b32_e32 v29, v48
	v_mov_b32_e32 v30, v48
	v_mov_b32_e32 v31, v48
	v_mov_b32_e32 v0, v48
	v_mov_b32_e32 v1, v48
	v_mov_b32_e32 v2, v48
	v_mov_b32_e32 v3, v48
	v_mov_b32_e32 v4, v48
	v_mov_b32_e32 v5, v48
	v_mov_b32_e32 v6, v48
	v_mov_b32_e32 v7, v48
	v_mov_b32_e32 v8, v48
	v_mov_b32_e32 v9, v48
	v_mov_b32_e32 v10, v48
	v_mov_b32_e32 v11, v48
	v_mov_b32_e32 v12, v48
	v_mov_b32_e32 v13, v48
	v_mov_b32_e32 v14, v48
	v_mov_b32_e32 v15, v48
	s_branch .LBB0_561

; #define LAS __attribute__((address_space(3)))
; __device__ __forceinline__ float bflo(unsigned w) { return __uint_as_float(w << 16); }
; __device__ __forceinline__ float bfhi(unsigned w) { return __uint_as_float(w & 0xffff0000u); }
; __device__ __forceinline__ float xsum(float v) { const auto r = __builtin_amdgcn_permlane32_swap(__float_as_uint(v), __float_as_uint(v), false, false); return __uint_as_float(r[0]) + __uint_as_float(r[1]); }
;     ...
;     float qn = 0.f; bool wdone = false;
;     LAS unsigned* flg = (LAS unsigned*)(lds + 2 * AT_BUF);
;     if (MODE == 0) {
; #pragma unroll
;         for (int ks = 0; ks < 8; ++ks) { const u32x4 qq = __builtin_bit_cast(u32x4, qf[ks]);
;             qn += bflo(qq.x) * bflo(qq.x) + bfhi(qq.x) * bfhi(qq.x) + bflo(qq.y) * bflo(qq.y) + bfhi(qq.y) * bfhi(qq.y) + bflo(qq.z) * bflo(qq.z) + bfhi(qq.z) * bfhi(qq.z) + bflo(qq.w) * bflo(qq.w) + bfhi(qq.w) * bfhi(qq.w); }
;         qn = xsum(qn); qn = sqrtf(qn) * kn * SC * 1.0001f + 1e-3f;
; __global__ void __launch_bounds__(512, 2) hybrid_fwd(Params p) {
;     ...
;                     const int qb = 31 - (u >> 2), hd = u & 3, tq0 = 256 * qb + 32 * wave, t_row = tq0 + (lane & 31);
;                     attn_unit<0>(lds, tid, PROJ + (size_t)t_row * NP + PJ_FQ + hd * 128, PROJ + PJ_FK + hd * 128, NP, VT + (size_t)(VT_F + hd * 128) * T_, T_,
;                                  0, 4 * (qb + 1), t_row, tq0, CC + (size_t)hd * T_, NEG, 0.f, nullptr, O + (size_t)t_row * D_ + hd * 128, sqrtf(__uint_as_float(KNB[l * 4 + hd])));
.LBB0_568:
	s_lshl_b32 s0, s2, 6
	s_and_b32 s12, s0, 0xffffff00
	s_lshl_b32 s0, s3, 5
	s_sub_i32 s13, s0, s12
	s_add_i32 s3, s13, 0x1f00
	s_and_b32 s14, s2, 3
	v_and_or_b32 v146, v144, 31, s3
	v_mov_b64_e32 v[0:1], s[8:9]
	v_mad_i64_i32 v[0:1], s[0:1], v146, s56, v[0:1]
	s_lshl_b32 s72, s14, 8
	s_add_u32 s0, s8, s72
	s_addc_u32 s1, s9, 0
	s_add_u32 s6, s0, 0x1f600400
	s_addc_u32 s7, s1, 0
	s_lshl_b32 s0, s14, 21
	s_add_u32 s0, s8, s0
	s_addc_u32 s1, s9, 0
	s_and_b32 s4, s2, -4
	s_lshl_b32 s5, s14, 15
	s_add_u32 s5, s8, s5
	s_addc_u32 s11, s9, 0
	s_add_u32 s10, s5, 0x38f00000
	v_lshl_add_u64 v[0:1], v[0:1], 0, s[72:73]
	s_addc_u32 s11, s11, 0
	s_or_b32 s72, s14, s20
	s_lshl_b64 s[16:17], s[72:73], 2
	s_add_u32 s5, s8, s16
	s_addc_u32 s15, s9, s17
	v_mov_b32_e32 v2, s5
	s_mov_b32 s5, 0x38f80000
	v_add_co_u32_e32 v2, vcc, s5, v2
	v_mov_b32_e32 v3, s15
	s_nop 0
	v_addc_co_u32_e32 v3, vcc, 0, v3, vcc
	v_mov_b32_e32 v145, v144
	flat_load_dword v6, v[2:3]
	s_mov_b64 s[16:17], 0x1f600000
	v_bfe_u32 v7, v145, 5, 1
	v_lshlrev_b32_e32 v200, 4, v7
	v_lshl_add_u64 v[0:1], v[0:1], 0, v[200:201]
	s_mov_b32 s5, 0x1f600000
	v_lshl_add_u64 v[2:3], v[0:1], 0, s[16:17]
	v_add_co_u32_e32 v0, vcc, s5, v0
	s_sub_i32 s15, 0x7f, s4
	s_nop 0
	v_addc_co_u32_e32 v1, vcc, 0, v1, vcc
	flat_load_dwordx4 v[96:99], v[0:1]
	flat_load_dwordx4 v[100:103], v[2:3] offset:32
	flat_load_dwordx4 v[104:107], v[2:3] offset:64
	flat_load_dwordx4 v[108:111], v[2:3] offset:96
	s_nop 0
	flat_load_dwordx4 v[112:115], v[2:3] offset:128
	flat_load_dwordx4 v[116:119], v[2:3] offset:160
	flat_load_dwordx4 v[120:123], v[2:3] offset:192
	flat_load_dwordx4 v[124:127], v[2:3] offset:224
	v_ashrrev_i32_e32 v168, 4, v145
	s_lshl_b32 s72, s15, 6
	v_and_b32_e32 v10, 15, v145
	v_ashrrev_i32_e32 v0, 3, v145
	v_lshlrev_b32_e32 v148, 4, v10
	v_mov_b32_e32 v149, v201
	v_and_b32_e32 v11, 7, v145
	v_lshlrev_b32_e32 v150, 4, v11
	v_mov_b32_e32 v151, v201
	s_waitcnt lgkmcnt(0)
	v_and_b32_e32 v2, 0xffff0000, v96
	v_lshlrev_b32_e32 v1, 16, v96
	v_mul_f32_e32 v2, v2, v2
	v_fmac_f32_e32 v2, v1, v1
	v_lshlrev_b32_e32 v1, 16, v97
	v_fmac_f32_e32 v2, v1, v1
	v_and_b32_e32 v1, 0xffff0000, v97
	v_fmac_f32_e32 v2, v1, v1
	v_lshlrev_b32_e32 v1, 16, v98
	v_fmac_f32_e32 v2, v1, v1
	v_and_b32_e32 v1, 0xffff0000, v98
	v_fmac_f32_e32 v2, v1, v1
	v_lshlrev_b32_e32 v1, 16, v99
	v_fmac_f32_e32 v2, v1, v1
	v_and_b32_e32 v1, 0xffff0000, v99
	v_and_b32_e32 v3, 0xffff0000, v100
	v_fmac_f32_e32 v2, v1, v1
	v_lshlrev_b32_e32 v1, 16, v100
	v_mul_f32_e32 v3, v3, v3
	v_fmac_f32_e32 v3, v1, v1
	v_lshlrev_b32_e32 v1, 16, v101
	v_fmac_f32_e32 v3, v1, v1
	v_and_b32_e32 v1, 0xffff0000, v101
	v_fmac_f32_e32 v3, v1, v1
	v_lshlrev_b32_e32 v1, 16, v102
	v_fmac_f32_e32 v3, v1, v1
	v_and_b32_e32 v1, 0xffff0000, v102
	v_fmac_f32_e32 v3, v1, v1
	v_lshlrev_b32_e32 v1, 16, v103
	v_fmac_f32_e32 v3, v1, v1
	v_and_b32_e32 v1, 0xffff0000, v103
	v_fmac_f32_e32 v3, v1, v1
	v_add_f32_e32 v1, v2, v3
	v_and_b32_e32 v3, 0xffff0000, v104
	v_lshlrev_b32_e32 v2, 16, v104
	v_mul_f32_e32 v3, v3, v3
	v_fmac_f32_e32 v3, v2, v2
	v_lshlrev_b32_e32 v2, 16, v105
	v_fmac_f32_e32 v3, v2, v2
	v_and_b32_e32 v2, 0xffff0000, v105
	v_fmac_f32_e32 v3, v2, v2
	v_lshlrev_b32_e32 v2, 16, v106
	v_fmac_f32_e32 v3, v2, v2
	v_and_b32_e32 v2, 0xffff0000, v106
	v_fmac_f32_e32 v3, v2, v2
	v_lshlrev_b32_e32 v2, 16, v107
	v_fmac_f32_e32 v3, v2, v2
	v_and_b32_e32 v2, 0xffff0000, v107
	v_fmac_f32_e32 v3, v2, v2
	v_add_f32_e32 v1, v1, v3
	v_and_b32_e32 v3, 0xffff0000, v108
	v_lshlrev_b32_e32 v2, 16, v108
	v_mul_f32_e32 v3, v3, v3
	v_fmac_f32_e32 v3, v2, v2
	v_lshlrev_b32_e32 v2, 16, v109
	v_fmac_f32_e32 v3, v2, v2
	v_and_b32_e32 v2, 0xffff0000, v109
	v_fmac_f32_e32 v3, v2, v2
	v_lshlrev_b32_e32 v2, 16, v110
	v_fmac_f32_e32 v3, v2, v2
	v_and_b32_e32 v2, 0xffff0000, v110
	v_fmac_f32_e32 v3, v2, v2
	v_lshlrev_b32_e32 v2, 16, v111
	v_fmac_f32_e32 v3, v2, v2
	v_and_b32_e32 v2, 0xffff0000, v111
	v_fmac_f32_e32 v3, v2, v2
	v_add_f32_e32 v1, v1, v3
	s_waitcnt vmcnt(0)
; #define LAS __attribute__((address_space(3)))
; __device__ __forceinline__ float bflo(unsigned w) { return __uint_as_float(w << 16); }
; __device__ __forceinline__ float bfhi(unsigned w) { return __uint_as_float(w & 0xffff0000u); }
; __device__ __forceinline__ float xsum(float v) { const auto r = __builtin_amdgcn_permlane32_swap(__float_as_uint(v), __float_as_uint(v), false, false); return __uint_as_float(r[0]) + __uint_as_float(r[1]); }
;     ...
;     float qn = 0.f; bool wdone = false;
;     LAS unsigned* flg = (LAS unsigned*)(lds + 2 * AT_BUF);
;     if (MODE == 0) {
; #pragma unroll
;         for (int ks = 0; ks < 8; ++ks) { const u32x4 qq = __builtin_bit_cast(u32x4, qf[ks]);
;             qn += bflo(qq.x) * bflo(qq.x) + bfhi(qq.x) * bfhi(qq.x) + bflo(qq.y) * bflo(qq.y) + bfhi(qq.y) * bfhi(qq.y) + bflo(qq.z) * bflo(qq.z) + bfhi(qq.z) * bfhi(qq.z) + bflo(qq.w) * bflo(qq.w) + bfhi(qq.w) * bfhi(qq.w); }
;         qn = xsum(qn); qn = sqrtf(qn) * kn * SC * 1.0001f + 1e-3f;
;     }
;     AT_LOAD(kt1 - 1); AT_WRITE(0); __syncthreads();
	v_and_b32_e32 v3, 0xffff0000, v112
	v_lshlrev_b32_e32 v2, 16, v112
	v_mul_f32_e32 v3, v3, v3
	v_fmac_f32_e32 v3, v2, v2
	v_lshlrev_b32_e32 v2, 16, v113
	v_fmac_f32_e32 v3, v2, v2
	v_and_b32_e32 v2, 0xffff0000, v113
	v_fmac_f32_e32 v3, v2, v2
	v_lshlrev_b32_e32 v2, 16, v114
	v_fmac_f32_e32 v3, v2, v2
	v_and_b32_e32 v2, 0xffff0000, v114
	v_fmac_f32_e32 v3, v2, v2
	v_lshlrev_b32_e32 v2, 16, v115
	v_fmac_f32_e32 v3, v2, v2
	v_and_b32_e32 v2, 0xffff0000, v115
	v_fmac_f32_e32 v3, v2, v2
	v_add_f32_e32 v1, v1, v3
	v_and_b32_e32 v3, 0xffff0000, v116
	v_lshlrev_b32_e32 v2, 16, v116
	v_mul_f32_e32 v3, v3, v3
	v_fmac_f32_e32 v3, v2, v2
	v_lshlrev_b32_e32 v2, 16, v117
	v_fmac_f32_e32 v3, v2, v2
	v_and_b32_e32 v2, 0xffff0000, v117
	v_fmac_f32_e32 v3, v2, v2
	v_lshlrev_b32_e32 v2, 16, v118
	v_fmac_f32_e32 v3, v2, v2
	v_and_b32_e32 v2, 0xffff0000, v118
	v_fmac_f32_e32 v3, v2, v2
	v_lshlrev_b32_e32 v2, 16, v119
	v_fmac_f32_e32 v3, v2, v2
	v_and_b32_e32 v2, 0xffff0000, v119
	v_fmac_f32_e32 v3, v2, v2
	v_add_f32_e32 v1, v1, v3
	v_and_b32_e32 v3, 0xffff0000, v120
	v_lshlrev_b32_e32 v2, 16, v120
	v_mul_f32_e32 v3, v3, v3
	v_fmac_f32_e32 v3, v2, v2
	v_lshlrev_b32_e32 v2, 16, v121
	v_fmac_f32_e32 v3, v2, v2
	v_and_b32_e32 v2, 0xffff0000, v121
	v_fmac_f32_e32 v3, v2, v2
	v_lshlrev_b32_e32 v2, 16, v122
	v_fmac_f32_e32 v3, v2, v2
	v_and_b32_e32 v2, 0xffff0000, v122
	v_fmac_f32_e32 v3, v2, v2
	v_lshlrev_b32_e32 v2, 16, v123
	v_fmac_f32_e32 v3, v2, v2
	v_and_b32_e32 v2, 0xffff0000, v123
	v_fmac_f32_e32 v3, v2, v2
	v_add_f32_e32 v1, v1, v3
	v_and_b32_e32 v3, 0xffff0000, v124
	v_lshlrev_b32_e32 v2, 16, v124
	v_mul_f32_e32 v3, v3, v3
	v_fmac_f32_e32 v3, v2, v2
	v_lshlrev_b32_e32 v2, 16, v125
	v_fmac_f32_e32 v3, v2, v2
	v_and_b32_e32 v2, 0xffff0000, v125
	v_fmac_f32_e32 v3, v2, v2
	v_lshlrev_b32_e32 v2, 16, v126
	v_fmac_f32_e32 v3, v2, v2
	v_and_b32_e32 v2, 0xffff0000, v126
	v_fmac_f32_e32 v3, v2, v2
	v_lshlrev_b32_e32 v2, 16, v127
	v_fmac_f32_e32 v3, v2, v2
	v_and_b32_e32 v2, 0xffff0000, v127
	v_fmac_f32_e32 v3, v2, v2
	v_add_f32_e32 v8, v1, v3
	v_add_u32_e32 v1, s72, v168
	v_mov_b64_e32 v[2:3], s[6:7]
	v_mad_i64_i32 v[4:5], s[4:5], v1, s56, v[2:3]
	v_add_u32_e32 v1, 32, v1
	v_mad_i64_i32 v[2:3], s[4:5], v1, s56, v[2:3]
	v_lshl_add_u64 v[4:5], v[4:5], 0, v[148:149]
	v_lshl_add_u64 v[2:3], v[2:3], 0, v[148:149]
	v_ashrrev_i32_e32 v1, 31, v0
	flat_load_dwordx4 v[128:131], v[4:5]
	flat_load_dwordx4 v[132:135], v[2:3]
	v_lshlrev_b64 v[2:3], 14, v[0:1]
	v_lshl_add_u64 v[4:5], s[0:1], 0, v[2:3]
	s_mov_b64 s[0:1], 0x22f00000
	v_lshl_add_u64 v[2:3], v[4:5], 0, s[0:1]
	s_lshl_b64 s[0:1], s[72:73], 1
	v_lshl_add_u64 v[12:13], v[2:3], 0, s[0:1]
	s_mov_b64 s[4:5], 0x23000000
	v_lshl_add_u64 v[12:13], v[12:13], 0, v[150:151]
	v_lshl_add_u64 v[4:5], v[4:5], 0, s[4:5]
	flat_load_dwordx4 v[136:139], v[12:13]
	v_lshl_add_u64 v[12:13], v[4:5], 0, s[0:1]
	v_lshl_add_u64 v[12:13], v[12:13], 0, v[150:151]
	flat_load_dwordx4 v[140:143], v[12:13]
	v_mov_b32_e32 v9, v8
	s_nop 1
	v_permlane32_swap_b32_e32 v8, v9
	v_cmp_gt_i32_e64 s[0:1], 64, v145
	v_mov_b32_e32 v149, 0
	s_and_saveexec_b64 s[4:5], s[0:1]
	s_cbranch_execz .LBB0_570
	v_add_u32_e32 v12, s72, v145
	v_ashrrev_i32_e32 v13, 31, v12
	v_lshl_add_u64 v[12:13], v[12:13], 2, s[10:11]
	flat_load_dword v149, v[12:13]
